# w_out EpiRes epilogue (both f32 layer-0 and bf16 residual paths) rewritten as straight-line load-ahead pipelines with counted vmcnt; stacked on mlp2 epilogue change
# speedup vs baseline: 1.0098x; 1.0098x over previous
.LBB0_556:
	v_lshrrev_b32_e32 v16, 1, v205
	s_add_u32 s69, s50, 0xd000000
	v_and_b32_e32 v16, 24, v16
	s_addc_u32 s78, s51, 0
	s_mul_i32 s1, s80, 0x24000
	v_and_b32_e32 v15, 15, v205
	v_lshlrev_b32_e32 v17, 1, v16
	s_add_u32 s79, s50, s1
	v_lshl_or_b32 v14, s0, 6, v15
	v_lshl_or_b32 v15, v15, 6, v17
	v_lshlrev_b32_e32 v17, 2, v205
	s_mov_b32 s92, s80
	s_addc_u32 s80, s51, 0
	s_lshl_b32 s0, s0, 13
	v_and_b32_e32 v17, 32, v17
	v_bitop3_b32 v18, v15, s0, v17 bitop3:0xde
	s_lshl_b32 s0, s14, 5
	s_and_b32 s4, s0, 0x60
	s_add_i32 m0, s61, 0x18000
	v_lshl_add_u64 v[6:7], v[6:7], 0, s[18:19]
	s_lshl_b32 s0, s4, 7
	s_waitcnt vmcnt(4)
	s_barrier
	global_load_lds_dwordx4 v[6:7], off
	v_lshl_add_u64 v[4:5], v[4:5], 0, s[18:19]
	s_add_i32 m0, s61, 0x1a000
	s_add_i32 s81, s61, 0x8000
	s_add_i32 s82, s61, 0xa000
	v_bitop3_b32 v206, s0, v15, v17 bitop3:0xf6
	global_load_lds_dwordx4 v[4:5], off
	v_lshl_add_u64 v[2:3], v[2:3], 0, s[18:19]
	s_mov_b32 m0, s81
	s_add_u32 s0, s38, 0x80080
	global_load_lds_dwordx4 v[2:3], off
	v_lshl_add_u64 v[0:1], v[0:1], 0, s[18:19]
	s_mov_b32 m0, s82
	s_addc_u32 s1, s39, 0
	global_load_lds_dwordx4 v[0:1], off
	s_add_i32 m0, s61, 0x1c000
	v_lshl_add_u64 v[0:1], s[0:1], 0, v[152:153]
	global_load_lds_dwordx4 v[0:1], off
	v_lshl_add_u64 v[0:1], s[0:1], 0, v[162:163]
	s_add_i32 m0, s61, 0x1e000
	v_ashrrev_i32_e32 v15, 31, v14
	global_load_lds_dwordx4 v[0:1], off
	v_or_b32_e32 v0, 16, v14
	v_ashrrev_i32_e32 v1, 31, v0
	v_lshlrev_b64 v[170:171], 11, v[0:1]
	v_or_b32_e32 v0, 32, v14
	v_ashrrev_i32_e32 v1, 31, v0
	v_lshlrev_b64 v[172:173], 11, v[0:1]
	v_or_b32_e32 v0, 48, v14
	v_ashrrev_i32_e32 v1, 31, v0
	v_lshlrev_b64 v[174:175], 11, v[0:1]
	v_lshlrev_b32_e32 v0, 15, v12
	v_and_b32_e32 v0, 0xffff0000, v0
	v_lshl_add_u32 v0, v11, 12, v0
	v_and_b32_e32 v1, 1, v12
	v_lshl_or_b32 v0, v1, 6, v0
	v_lshlrev_b64 v[168:169], 11, v[14:15]
	s_mov_b64 s[0:1], 0x40000
	v_lshl_add_u32 v184, v13, 1, v0
	v_lshlrev_b32_e32 v0, 15, v8
	v_lshl_add_u64 v[176:177], v[168:169], 0, s[0:1]
	s_mov_b64 s[0:1], 0x48000
	v_and_b32_e32 v0, 0xffff0000, v0
	s_waitcnt vmcnt(6)
	v_lshl_add_u64 v[178:179], v[168:169], 0, s[0:1]
	s_mov_b64 s[0:1], 0x50000
	v_lshl_add_u32 v0, v9, 12, v0
	v_and_b32_e32 v1, 1, v8
	v_lshl_add_u64 v[180:181], v[168:169], 0, s[0:1]
	s_mov_b64 s[0:1], 0x58000
	v_lshl_or_b32 v0, v1, 6, v0
	v_lshl_add_u64 v[182:183], v[168:169], 0, s[0:1]
	v_or_b32_e32 v207, s4, v16
	v_mov_b32_e32 v185, v153
	v_lshl_add_u32 v186, v10, 1, v0
	v_mov_b32_e32 v187, v153
	s_mov_b32 s83, 0
	v_add_u32_e32 v208, 0, v18
	v_readlane_b32 s4, v253, 19
	v_readlane_b32 s20, v253, 30
	s_barrier
	v_readlane_b32 s21, v253, 31
	s_branch .LBB0_558
.LBB0_558:
	s_add_i32 s83, s83, 1
	s_mul_i32 s1, s83, s3
	s_mul_hi_u32 s5, s83, s66
	s_add_i32 s5, s5, s1
	s_mul_i32 s1, s83, s66
	s_add_u32 s24, s1, s2
	s_addc_u32 s25, s5, s33
	v_cmp_gt_i64_e64 s[42:43], s[24:25], v[158:159]
	s_and_b64 vcc, exec, s[42:43]
	s_cbranch_vccnz .LBB0_560
	s_ashr_i32 s0, s24, 31
	s_lshr_b32 s0, s0, 29
	s_add_i32 s0, s24, s0
	s_ashr_i32 s1, s0, 3
	s_and_b32 s0, s0, -8
	s_sub_i32 s0, s24, s0
	s_cmp_lt_i32 s0, 0
	s_cselect_b32 s5, 49, 48
	s_mul_i32 s0, s0, s5
	s_add_i32 s0, s0, s1
	s_ashr_i32 s1, s0, 31
	s_lshr_b32 s1, s1, 26
	s_add_i32 s1, s0, s1
	s_ashr_i32 s5, s1, 6
	s_lshl_b32 s5, s5, 3
	s_sub_i32 s6, 48, s5
	s_min_i32 s6, s6, 8
	s_abs_i32 s7, s6
	v_cvt_f32_u32_e32 v0, s7
	s_sub_i32 s17, 0, s7
	s_andn2_b32 s1, s1, 63
	s_sub_i32 s1, s0, s1
	v_rcp_iflag_f32_e32 v0, v0
	s_abs_i32 s0, s1
	s_xor_b32 s16, s1, s6
	s_ashr_i32 s16, s16, 31
	v_mul_f32_e32 v0, 0x4f7ffffe, v0
	v_cvt_u32_f32_e32 v0, v0
	s_nop 0
	v_readfirstlane_b32 s21, v0
	s_mul_i32 s17, s17, s21
	s_mul_hi_u32 s17, s21, s17
	s_add_i32 s21, s21, s17
	s_mul_hi_u32 s17, s0, s21
	s_mul_i32 s21, s17, s7
	s_sub_i32 s0, s0, s21
	s_add_i32 s30, s17, 1
	s_sub_i32 s21, s0, s7
	s_cmp_ge_u32 s0, s7
	s_cselect_b32 s17, s30, s17
	s_cselect_b32 s0, s21, s0
	s_add_i32 s21, s17, 1
	s_cmp_ge_u32 s0, s7
	s_cselect_b32 s0, s21, s17
	s_xor_b32 s0, s0, s16
	s_sub_i32 s0, s0, s16
	s_mul_i32 s6, s0, s6
	s_sub_i32 s1, s1, s6
	s_add_i32 s16, s5, s1

.LBB0_561:
	s_add_u32 s38, s22, 0xfff80080
	s_addc_u32 s39, s23, -1
	s_add_i32 s84, 0, 0x10000
	v_add_u32_e32 v92, s84, v206
	ds_read_b128 v[72:75], v92
	ds_read_b128 v[76:79], v92 offset:1024
	ds_read_b128 v[84:87], v92 offset:2048
	ds_read_b128 v[92:95], v92 offset:3072
	s_cmp_eq_u32 s30, 28
	s_cselect_b32 s53, s5, s39
	s_cselect_b32 s52, s6, s38
	s_cselect_b32 s39, s1, s21
	s_cselect_b32 s38, s7, s17
	v_lshl_add_u64 v[192:193], s[22:23], 0, v[184:185]
	s_add_i32 m0, s61, 0xc000
	ds_read_b128 v[144:147], v208
	ds_read_b128 v[148:151], v208 offset:1024
	ds_read_b128 v[188:191], v208 offset:2048
	ds_read_b128 v[210:213], v208 offset:3072
	ds_read_b128 v[214:217], v208 offset:4096
	ds_read_b128 v[218:221], v208 offset:5120
	ds_read_b128 v[222:225], v208 offset:6144
	ds_read_b128 v[226:229], v208 offset:7168
	global_load_lds_dwordx4 v[192:193], off
	v_lshl_add_u64 v[192:193], s[22:23], 0, v[186:187]
	s_add_i32 m0, s61, 0xe000
	s_nop 0
	global_load_lds_dwordx4 v[192:193], off
	s_waitcnt lgkmcnt(8)
	s_barrier
	s_waitcnt lgkmcnt(0)
	s_setprio 1
	s_waitcnt lgkmcnt(0)
	v_mfma_f32_16x16x32_bf16 v[140:143], v[72:75], v[144:147], v[140:143]
	v_mfma_f32_16x16x32_bf16 v[136:139], v[84:87], v[144:147], v[136:139]
	v_mfma_f32_16x16x32_bf16 v[124:127], v[72:75], v[188:191], v[124:127]
	v_mfma_f32_16x16x32_bf16 v[120:123], v[84:87], v[188:191], v[120:123]
	v_mfma_f32_16x16x32_bf16 v[108:111], v[72:75], v[214:217], v[108:111]
	v_mfma_f32_16x16x32_bf16 v[104:107], v[84:87], v[214:217], v[104:107]
	v_mfma_f32_16x16x32_bf16 v[88:91], v[72:75], v[222:225], v[88:91]
	v_mfma_f32_16x16x32_bf16 v[80:83], v[84:87], v[222:225], v[80:83]
	v_mfma_f32_16x16x32_bf16 v[140:143], v[76:79], v[148:151], v[140:143]
	v_mfma_f32_16x16x32_bf16 v[136:139], v[92:95], v[148:151], v[136:139]
	v_mfma_f32_16x16x32_bf16 v[124:127], v[76:79], v[210:213], v[124:127]
	v_mfma_f32_16x16x32_bf16 v[120:123], v[92:95], v[210:213], v[120:123]
	v_mfma_f32_16x16x32_bf16 v[108:111], v[76:79], v[218:221], v[108:111]
	v_mfma_f32_16x16x32_bf16 v[104:107], v[92:95], v[218:221], v[104:107]
	v_mfma_f32_16x16x32_bf16 v[88:91], v[76:79], v[226:229], v[88:91]
	v_mfma_f32_16x16x32_bf16 v[80:83], v[92:95], v[226:229], v[80:83]
	s_setprio 0
	s_barrier
	s_add_i32 s86, 0, 0x14000
	v_add_u32_e32 v192, s86, v206
	s_add_i32 s84, s84, s60
	ds_read_b128 v[230:233], v192
	ds_read_b128 v[234:237], v192 offset:1024
	ds_read_b128 v[238:241], v192 offset:2048
	ds_read_b128 v[242:245], v192 offset:3072
	v_lshl_add_u64 v[192:193], s[38:39], 0, v[152:153]
	s_mov_b32 m0, s84
	v_lshl_add_u64 v[246:247], s[38:39], 0, v[162:163]
	global_load_lds_dwordx4 v[192:193], off
	s_add_i32 m0, s84, 0x2000
	s_nop 0
	global_load_lds_dwordx4 v[246:247], off
	s_barrier
	s_waitcnt lgkmcnt(0)
	s_setprio 1
	s_waitcnt lgkmcnt(0)
	v_mfma_f32_16x16x32_bf16 v[132:135], v[230:233], v[144:147], v[132:135]
	v_mfma_f32_16x16x32_bf16 v[128:131], v[238:241], v[144:147], v[128:131]
	v_mfma_f32_16x16x32_bf16 v[116:119], v[230:233], v[188:191], v[116:119]
	v_mfma_f32_16x16x32_bf16 v[112:115], v[238:241], v[188:191], v[112:115]
	v_mfma_f32_16x16x32_bf16 v[100:103], v[230:233], v[214:217], v[100:103]
	v_mfma_f32_16x16x32_bf16 v[96:99], v[238:241], v[214:217], v[96:99]
	v_mfma_f32_16x16x32_bf16 v[68:71], v[230:233], v[222:225], v[68:71]
	v_mfma_f32_16x16x32_bf16 v[64:67], v[238:241], v[222:225], v[64:67]
	v_mfma_f32_16x16x32_bf16 v[132:135], v[234:237], v[148:151], v[132:135]
	v_mfma_f32_16x16x32_bf16 v[128:131], v[242:245], v[148:151], v[128:131]
	v_mfma_f32_16x16x32_bf16 v[116:119], v[234:237], v[210:213], v[116:119]
	v_mfma_f32_16x16x32_bf16 v[112:115], v[242:245], v[210:213], v[112:115]
	v_mfma_f32_16x16x32_bf16 v[100:103], v[234:237], v[218:221], v[100:103]
	v_mfma_f32_16x16x32_bf16 v[96:99], v[242:245], v[218:221], v[96:99]
	v_mfma_f32_16x16x32_bf16 v[68:71], v[234:237], v[226:229], v[68:71]
	v_mfma_f32_16x16x32_bf16 v[64:67], v[242:245], v[226:229], v[64:67]
	s_setprio 0
	s_mov_b32 m0, s61
	v_lshl_add_u64 v[248:249], s[52:53], 0, v[166:167]
	s_barrier
	ds_read_b128 v[144:147], v208 offset:16384
	ds_read_b128 v[148:151], v208 offset:17408
	ds_read_b128 v[188:191], v208 offset:18432
	ds_read_b128 v[210:213], v208 offset:19456
	ds_read_b128 v[214:217], v208 offset:20480
	ds_read_b128 v[218:221], v208 offset:21504
	ds_read_b128 v[222:225], v208 offset:22528
	ds_read_b128 v[226:229], v208 offset:23552
	global_load_lds_dwordx4 v[248:249], off
	v_lshl_add_u64 v[250:251], s[52:53], 0, v[164:165]
	s_mov_b32 m0, s62
	s_nop 0
	global_load_lds_dwordx4 v[250:251], off
	s_barrier
	s_waitcnt lgkmcnt(0)
	s_setprio 1
	s_waitcnt lgkmcnt(0)
	v_mfma_f32_16x16x32_bf16 v[60:63], v[72:75], v[144:147], v[60:63]
	v_mfma_f32_16x16x32_bf16 v[56:59], v[84:87], v[144:147], v[56:59]
	v_mfma_f32_16x16x32_bf16 v[44:47], v[72:75], v[188:191], v[44:47]
	v_mfma_f32_16x16x32_bf16 v[40:43], v[84:87], v[188:191], v[40:43]
	v_mfma_f32_16x16x32_bf16 v[28:31], v[72:75], v[214:217], v[28:31]
	v_mfma_f32_16x16x32_bf16 v[24:27], v[84:87], v[214:217], v[24:27]
	v_mfma_f32_16x16x32_bf16 v[12:15], v[72:75], v[222:225], v[12:15]
	v_mfma_f32_16x16x32_bf16 v[8:11], v[84:87], v[222:225], v[8:11]
	v_mfma_f32_16x16x32_bf16 v[60:63], v[76:79], v[148:151], v[60:63]
	v_mfma_f32_16x16x32_bf16 v[56:59], v[92:95], v[148:151], v[56:59]
	v_mfma_f32_16x16x32_bf16 v[44:47], v[76:79], v[210:213], v[44:47]
	v_mfma_f32_16x16x32_bf16 v[40:43], v[92:95], v[210:213], v[40:43]
	v_mfma_f32_16x16x32_bf16 v[28:31], v[76:79], v[218:221], v[28:31]
	v_mfma_f32_16x16x32_bf16 v[24:27], v[92:95], v[218:221], v[24:27]
	v_mfma_f32_16x16x32_bf16 v[12:15], v[76:79], v[226:229], v[12:15]
	v_mfma_f32_16x16x32_bf16 v[8:11], v[92:95], v[226:229], v[8:11]
	s_setprio 0
	s_barrier
	s_add_u32 s84, s38, 0x80000
	s_addc_u32 s85, s39, 0
	s_add_i32 s86, s86, s60
	v_lshl_add_u64 v[72:73], s[84:85], 0, v[152:153]
	s_mov_b32 m0, s86
	s_nop 0
	global_load_lds_dwordx4 v[72:73], off
	v_lshl_add_u64 v[72:73], s[84:85], 0, v[162:163]
	s_add_i32 m0, s86, 0x2000
	s_nop 0
	global_load_lds_dwordx4 v[72:73], off
	s_waitcnt vmcnt(6)
	s_barrier
	s_setprio 1
	v_mfma_f32_16x16x32_bf16 v[52:55], v[230:233], v[144:147], v[52:55]
	v_mfma_f32_16x16x32_bf16 v[48:51], v[238:241], v[144:147], v[48:51]
	v_mfma_f32_16x16x32_bf16 v[36:39], v[230:233], v[188:191], v[36:39]
	v_mfma_f32_16x16x32_bf16 v[32:35], v[238:241], v[188:191], v[32:35]
	v_mfma_f32_16x16x32_bf16 v[20:23], v[230:233], v[214:217], v[20:23]
	v_mfma_f32_16x16x32_bf16 v[16:19], v[238:241], v[214:217], v[16:19]
	v_mfma_f32_16x16x32_bf16 v[4:7], v[230:233], v[222:225], v[4:7]
	v_mfma_f32_16x16x32_bf16 v[0:3], v[238:241], v[222:225], v[0:3]
	v_mfma_f32_16x16x32_bf16 v[52:55], v[234:237], v[148:151], v[52:55]
	v_mfma_f32_16x16x32_bf16 v[48:51], v[242:245], v[148:151], v[48:51]
	v_mfma_f32_16x16x32_bf16 v[36:39], v[234:237], v[210:213], v[36:39]
	v_mfma_f32_16x16x32_bf16 v[32:35], v[242:245], v[210:213], v[32:35]
	v_mfma_f32_16x16x32_bf16 v[20:23], v[234:237], v[218:221], v[20:23]
	v_mfma_f32_16x16x32_bf16 v[16:19], v[242:245], v[218:221], v[16:19]
	v_mfma_f32_16x16x32_bf16 v[4:7], v[234:237], v[226:229], v[4:7]
	v_mfma_f32_16x16x32_bf16 v[0:3], v[242:245], v[226:229], v[0:3]
	s_setprio 0
	s_add_i32 s84, 0, 0x18000
	v_add_u32_e32 v92, s84, v206
	s_barrier
	ds_read_b128 v[72:75], v92
	ds_read_b128 v[76:79], v92 offset:1024
	ds_read_b128 v[84:87], v92 offset:2048
	ds_read_b128 v[92:95], v92 offset:3072
	s_add_u32 s52, s52, 0x80000
	s_addc_u32 s53, s53, 0
	s_mov_b32 m0, s63
	v_lshl_add_u64 v[230:231], s[52:53], 0, v[166:167]
	ds_read_b128 v[144:147], v208 offset:32768
	ds_read_b128 v[148:151], v208 offset:33792
	ds_read_b128 v[188:191], v208 offset:34816
	ds_read_b128 v[210:213], v208 offset:35840
	ds_read_b128 v[214:217], v208 offset:36864
	ds_read_b128 v[218:221], v208 offset:37888
	ds_read_b128 v[222:225], v208 offset:38912
	ds_read_b128 v[226:229], v208 offset:39936
	global_load_lds_dwordx4 v[230:231], off
	v_lshl_add_u64 v[230:231], s[52:53], 0, v[164:165]
	s_mov_b32 m0, s68
	s_nop 0
	global_load_lds_dwordx4 v[230:231], off
	s_waitcnt lgkmcnt(8)
	s_barrier
	s_waitcnt lgkmcnt(0)
	s_setprio 1
	s_waitcnt lgkmcnt(0)
	v_mfma_f32_16x16x32_bf16 v[140:143], v[72:75], v[144:147], v[140:143]
	v_mfma_f32_16x16x32_bf16 v[136:139], v[84:87], v[144:147], v[136:139]
	v_mfma_f32_16x16x32_bf16 v[124:127], v[72:75], v[188:191], v[124:127]
	v_mfma_f32_16x16x32_bf16 v[120:123], v[84:87], v[188:191], v[120:123]
	v_mfma_f32_16x16x32_bf16 v[108:111], v[72:75], v[214:217], v[108:111]
	v_mfma_f32_16x16x32_bf16 v[104:107], v[84:87], v[214:217], v[104:107]
	v_mfma_f32_16x16x32_bf16 v[88:91], v[72:75], v[222:225], v[88:91]
	v_mfma_f32_16x16x32_bf16 v[80:83], v[84:87], v[222:225], v[80:83]
	v_mfma_f32_16x16x32_bf16 v[140:143], v[76:79], v[148:151], v[140:143]
	v_mfma_f32_16x16x32_bf16 v[136:139], v[92:95], v[148:151], v[136:139]
	v_mfma_f32_16x16x32_bf16 v[124:127], v[76:79], v[210:213], v[124:127]
	v_mfma_f32_16x16x32_bf16 v[120:123], v[92:95], v[210:213], v[120:123]
	v_mfma_f32_16x16x32_bf16 v[108:111], v[76:79], v[218:221], v[108:111]
	v_mfma_f32_16x16x32_bf16 v[104:107], v[92:95], v[218:221], v[104:107]
	v_mfma_f32_16x16x32_bf16 v[88:91], v[76:79], v[226:229], v[88:91]
	v_mfma_f32_16x16x32_bf16 v[80:83], v[92:95], v[226:229], v[80:83]
	s_setprio 0
	s_barrier
	s_add_i32 s52, 0, 0x1c000
	s_add_i32 s53, s84, s60
	v_add_u32_e32 v209, s52, v206
	v_lshl_add_u64 v[192:193], v[192:193], 0, s[18:19]
	s_mov_b32 m0, s53
	ds_read_b128 v[230:233], v209
	ds_read_b128 v[234:237], v209 offset:1024
	ds_read_b128 v[238:241], v209 offset:2048
	ds_read_b128 v[242:245], v209 offset:3072
	global_load_lds_dwordx4 v[192:193], off
	v_lshl_add_u64 v[192:193], v[246:247], 0, s[18:19]
	s_add_i32 m0, s53, 0x2000
	s_nop 0
	global_load_lds_dwordx4 v[192:193], off
	s_barrier
	s_waitcnt lgkmcnt(0)
	s_setprio 1
	s_waitcnt lgkmcnt(0)
	v_mfma_f32_16x16x32_bf16 v[132:135], v[230:233], v[144:147], v[132:135]
	v_mfma_f32_16x16x32_bf16 v[128:131], v[238:241], v[144:147], v[128:131]
	v_mfma_f32_16x16x32_bf16 v[116:119], v[230:233], v[188:191], v[116:119]
	v_mfma_f32_16x16x32_bf16 v[112:115], v[238:241], v[188:191], v[112:115]
	v_mfma_f32_16x16x32_bf16 v[100:103], v[230:233], v[214:217], v[100:103]
	v_mfma_f32_16x16x32_bf16 v[96:99], v[238:241], v[214:217], v[96:99]
	v_mfma_f32_16x16x32_bf16 v[68:71], v[230:233], v[222:225], v[68:71]
	v_mfma_f32_16x16x32_bf16 v[64:67], v[238:241], v[222:225], v[64:67]
	v_mfma_f32_16x16x32_bf16 v[132:135], v[234:237], v[148:151], v[132:135]
	v_mfma_f32_16x16x32_bf16 v[128:131], v[242:245], v[148:151], v[128:131]
	v_mfma_f32_16x16x32_bf16 v[116:119], v[234:237], v[210:213], v[116:119]
	v_mfma_f32_16x16x32_bf16 v[112:115], v[242:245], v[210:213], v[112:115]
	v_mfma_f32_16x16x32_bf16 v[100:103], v[234:237], v[218:221], v[100:103]
	v_mfma_f32_16x16x32_bf16 v[96:99], v[242:245], v[218:221], v[96:99]
	v_mfma_f32_16x16x32_bf16 v[68:71], v[234:237], v[226:229], v[68:71]
	v_mfma_f32_16x16x32_bf16 v[64:67], v[242:245], v[226:229], v[64:67]
	s_setprio 0
	s_mov_b32 m0, s81
	v_lshl_add_u64 v[192:193], v[248:249], 0, s[18:19]
	s_barrier
	ds_read_b128 v[144:147], v208 offset:49152
	ds_read_b128 v[148:151], v208 offset:50176
	ds_read_b128 v[188:191], v208 offset:51200
	ds_read_b128 v[210:213], v208 offset:52224
	ds_read_b128 v[214:217], v208 offset:53248
	ds_read_b128 v[218:221], v208 offset:54272
	ds_read_b128 v[222:225], v208 offset:55296
	ds_read_b128 v[226:229], v208 offset:56320
	global_load_lds_dwordx4 v[192:193], off
	v_lshl_add_u64 v[192:193], v[250:251], 0, s[18:19]
	s_mov_b32 m0, s82
	s_nop 0
	global_load_lds_dwordx4 v[192:193], off
	s_barrier
	s_waitcnt lgkmcnt(0)
	s_setprio 1
	s_waitcnt lgkmcnt(0)
	v_mfma_f32_16x16x32_bf16 v[60:63], v[72:75], v[144:147], v[60:63]
	v_mfma_f32_16x16x32_bf16 v[56:59], v[84:87], v[144:147], v[56:59]
	v_mfma_f32_16x16x32_bf16 v[44:47], v[72:75], v[188:191], v[44:47]
	v_mfma_f32_16x16x32_bf16 v[40:43], v[84:87], v[188:191], v[40:43]
	v_mfma_f32_16x16x32_bf16 v[28:31], v[72:75], v[214:217], v[28:31]
	v_mfma_f32_16x16x32_bf16 v[24:27], v[84:87], v[214:217], v[24:27]
	v_mfma_f32_16x16x32_bf16 v[12:15], v[72:75], v[222:225], v[12:15]
	v_mfma_f32_16x16x32_bf16 v[8:11], v[84:87], v[222:225], v[8:11]
	v_mfma_f32_16x16x32_bf16 v[60:63], v[76:79], v[148:151], v[60:63]
	v_mfma_f32_16x16x32_bf16 v[56:59], v[92:95], v[148:151], v[56:59]
	v_mfma_f32_16x16x32_bf16 v[44:47], v[76:79], v[210:213], v[44:47]
	v_mfma_f32_16x16x32_bf16 v[40:43], v[92:95], v[210:213], v[40:43]
	v_mfma_f32_16x16x32_bf16 v[28:31], v[76:79], v[218:221], v[28:31]
	v_mfma_f32_16x16x32_bf16 v[24:27], v[92:95], v[218:221], v[24:27]
	v_mfma_f32_16x16x32_bf16 v[12:15], v[76:79], v[226:229], v[12:15]
	v_mfma_f32_16x16x32_bf16 v[8:11], v[92:95], v[226:229], v[8:11]
	s_setprio 0
	s_barrier
	s_add_u32 s38, s38, 0x80080
	s_addc_u32 s39, s39, 0
	s_add_i32 s52, s52, s60
	v_lshl_add_u64 v[72:73], s[38:39], 0, v[152:153]
	s_mov_b32 m0, s52
	s_nop 0
	global_load_lds_dwordx4 v[72:73], off
	v_lshl_add_u64 v[72:73], s[38:39], 0, v[162:163]
	s_add_i32 m0, s52, 0x2000
	s_nop 0
	global_load_lds_dwordx4 v[72:73], off
	s_waitcnt vmcnt(6)
	s_barrier
	s_setprio 1
	v_mfma_f32_16x16x32_bf16 v[52:55], v[230:233], v[144:147], v[52:55]
	v_mfma_f32_16x16x32_bf16 v[48:51], v[238:241], v[144:147], v[48:51]
	v_mfma_f32_16x16x32_bf16 v[36:39], v[230:233], v[188:191], v[36:39]
	v_mfma_f32_16x16x32_bf16 v[32:35], v[238:241], v[188:191], v[32:35]
	v_mfma_f32_16x16x32_bf16 v[20:23], v[230:233], v[214:217], v[20:23]
	v_mfma_f32_16x16x32_bf16 v[16:19], v[238:241], v[214:217], v[16:19]
	v_mfma_f32_16x16x32_bf16 v[4:7], v[230:233], v[222:225], v[4:7]
	v_mfma_f32_16x16x32_bf16 v[0:3], v[238:241], v[222:225], v[0:3]
	v_mfma_f32_16x16x32_bf16 v[52:55], v[234:237], v[148:151], v[52:55]
	v_mfma_f32_16x16x32_bf16 v[48:51], v[242:245], v[148:151], v[48:51]
	v_mfma_f32_16x16x32_bf16 v[36:39], v[234:237], v[210:213], v[36:39]
	v_mfma_f32_16x16x32_bf16 v[32:35], v[242:245], v[210:213], v[32:35]
	v_mfma_f32_16x16x32_bf16 v[20:23], v[234:237], v[218:221], v[20:23]
	v_mfma_f32_16x16x32_bf16 v[16:19], v[242:245], v[218:221], v[16:19]
	v_mfma_f32_16x16x32_bf16 v[4:7], v[234:237], v[226:229], v[4:7]
	v_mfma_f32_16x16x32_bf16 v[0:3], v[242:245], v[226:229], v[0:3]
	s_setprio 0
	s_add_i32 s30, s30, 2
	s_add_u32 s22, s22, 0x100
	s_addc_u32 s23, s23, 0
	s_add_u32 s17, s17, 0x100
	s_addc_u32 s21, s21, 0
	s_cmp_gt_u32 s30, 29
	s_barrier
	s_cbranch_scc0 .LBB0_561
	v_lshl_or_b32 v188, s4, 8, v207
	v_ashrrev_i32_e32 v189, 31, v188
	s_cmp_lt_i32 s20, 16
	s_cselect_b32 s6, s44, s46
	s_cselect_b32 s7, s45, s47
	s_cselect_b32 s1, 0, 16
	s_sub_i32 s4, s20, s1
	s_mov_b32 s5, 0
	s_lshl_b64 s[4:5], s[4:5], 21
	s_add_u32 s38, s6, s4
	s_addc_u32 s39, s7, s5
	s_cmp_lt_i32 s20, 32
	s_cselect_b32 s1, 0x3000, s73
	s_cmp_lt_i32 s20, 16
	s_cselect_b32 s1, 0, s1
	s_lshl_b32 s1, s1, 2
	s_add_u32 s6, s79, s1
	s_addc_u32 s7, s80, 0
	s_mov_b32 s4, s20
	s_mov_b32 s5, 0
	s_lshl_b64 s[4:5], s[4:5], 20
	s_add_u32 s52, s69, s4
	s_addc_u32 s53, s78, s5
	v_lshl_add_u64 v[190:191], v[188:189], 2, s[6:7]
	s_mov_b64 s[4:5], 0x28504000
	v_lshl_add_u64 v[190:191], v[190:191], 0, s[4:5]
	global_load_dwordx4 v[92:95], v[190:191], off
	global_load_dwordx4 v[84:87], v[190:191], off offset:16
	global_load_dwordx4 v[76:79], v[190:191], off offset:512
	global_load_dwordx4 v[72:75], v[190:191], off offset:528
	v_lshl_add_u64 v[144:145], v[188:189], 1, s[52:53]
	s_and_b64 vcc, exec, s[64:65]
	s_cbranch_vccz .Lwo_epi_f32
	v_lshl_add_u64 v[148:149], v[168:169], 1, v[144:145]
	global_load_dwordx4 v[210:213], v[148:149], off
	global_load_dwordx4 v[214:217], v[148:149], off offset:256
	v_lshl_add_u64 v[148:149], v[170:171], 1, v[144:145]
	global_load_dwordx4 v[218:221], v[148:149], off
	global_load_dwordx4 v[222:225], v[148:149], off offset:256
	v_lshl_add_u64 v[148:149], v[172:173], 1, v[144:145]
	global_load_dwordx4 v[226:229], v[148:149], off
	global_load_dwordx4 v[230:233], v[148:149], off offset:256
	v_lshl_add_u64 v[148:149], v[174:175], 1, v[144:145]
	global_load_dwordx4 v[234:237], v[148:149], off
	global_load_dwordx4 v[238:241], v[148:149], off offset:256
	v_lshl_add_u64 v[148:149], v[176:177], 1, v[144:145]
	global_load_dwordx4 v[242:245], v[148:149], off
	s_waitcnt vmcnt(8)
	v_lshlrev_b32_e32 v188, 16, v210
	v_and_b32_e32 v189, 0xffff0000, v210
	v_lshlrev_b32_e32 v190, 16, v211
	v_and_b32_e32 v191, 0xffff0000, v211
	v_lshlrev_b32_e32 v246, 16, v212
	v_and_b32_e32 v247, 0xffff0000, v212
	v_lshlrev_b32_e32 v248, 16, v213
	v_and_b32_e32 v249, 0xffff0000, v213
	global_load_dwordx4 v[210:213], v[148:149], off offset:256
	v_lshl_add_u64 v[150:151], v[168:169], 1, v[144:145]
	v_pk_fma_f32 v[140:141], v[140:141], v[92:93], v[188:189]
	v_pk_fma_f32 v[142:143], v[142:143], v[94:95], v[190:191]
	v_pk_fma_f32 v[136:137], v[136:137], v[84:85], v[246:247]
	v_pk_fma_f32 v[138:139], v[138:139], v[86:87], v[248:249]
	v_cvt_pk_bf16_f32 v140, v140, v141
	v_cvt_pk_bf16_f32 v141, v142, v143
	v_cvt_pk_bf16_f32 v142, v136, v137
	v_cvt_pk_bf16_f32 v143, v138, v139
	global_store_dwordx4 v[150:151], v[140:143], off
	s_waitcnt vmcnt(9)
	v_lshlrev_b32_e32 v188, 16, v214
	v_and_b32_e32 v189, 0xffff0000, v214
	v_lshlrev_b32_e32 v190, 16, v215
	v_and_b32_e32 v191, 0xffff0000, v215
	v_lshlrev_b32_e32 v246, 16, v216
	v_and_b32_e32 v247, 0xffff0000, v216
	v_lshlrev_b32_e32 v248, 16, v217
	v_and_b32_e32 v249, 0xffff0000, v217
	v_lshl_add_u64 v[148:149], v[178:179], 1, v[144:145]
	global_load_dwordx4 v[214:217], v[148:149], off
	v_pk_fma_f32 v[132:133], v[132:133], v[76:77], v[188:189]
	v_pk_fma_f32 v[134:135], v[134:135], v[78:79], v[190:191]
	v_pk_fma_f32 v[128:129], v[128:129], v[72:73], v[246:247]
	v_pk_fma_f32 v[130:131], v[130:131], v[74:75], v[248:249]
	v_cvt_pk_bf16_f32 v132, v132, v133
	v_cvt_pk_bf16_f32 v133, v134, v135
	v_cvt_pk_bf16_f32 v134, v128, v129
	v_cvt_pk_bf16_f32 v135, v130, v131
	global_store_dwordx4 v[150:151], v[132:135], off offset:256
	s_waitcnt vmcnt(10)
	v_lshlrev_b32_e32 v188, 16, v218
	v_and_b32_e32 v189, 0xffff0000, v218
	v_lshlrev_b32_e32 v190, 16, v219
	v_and_b32_e32 v191, 0xffff0000, v219
	v_lshlrev_b32_e32 v246, 16, v220
	v_and_b32_e32 v247, 0xffff0000, v220
	v_lshlrev_b32_e32 v248, 16, v221
	v_and_b32_e32 v249, 0xffff0000, v221
	global_load_dwordx4 v[218:221], v[148:149], off offset:256
	v_lshl_add_u64 v[192:193], v[170:171], 1, v[144:145]
	v_pk_fma_f32 v[124:125], v[124:125], v[92:93], v[188:189]
	v_pk_fma_f32 v[126:127], v[126:127], v[94:95], v[190:191]
	v_pk_fma_f32 v[120:121], v[120:121], v[84:85], v[246:247]
	v_pk_fma_f32 v[122:123], v[122:123], v[86:87], v[248:249]
	v_cvt_pk_bf16_f32 v124, v124, v125
	v_cvt_pk_bf16_f32 v125, v126, v127
	v_cvt_pk_bf16_f32 v126, v120, v121
	v_cvt_pk_bf16_f32 v127, v122, v123
	global_store_dwordx4 v[192:193], v[124:127], off
	s_waitcnt vmcnt(11)
	v_lshlrev_b32_e32 v188, 16, v222
	v_and_b32_e32 v189, 0xffff0000, v222
	v_lshlrev_b32_e32 v190, 16, v223
	v_and_b32_e32 v191, 0xffff0000, v223
	v_lshlrev_b32_e32 v246, 16, v224
	v_and_b32_e32 v247, 0xffff0000, v224
	v_lshlrev_b32_e32 v248, 16, v225
	v_and_b32_e32 v249, 0xffff0000, v225
	v_lshl_add_u64 v[148:149], v[180:181], 1, v[144:145]
	global_load_dwordx4 v[222:225], v[148:149], off
	v_pk_fma_f32 v[116:117], v[116:117], v[76:77], v[188:189]
	v_pk_fma_f32 v[118:119], v[118:119], v[78:79], v[190:191]
	v_pk_fma_f32 v[112:113], v[112:113], v[72:73], v[246:247]
	v_pk_fma_f32 v[114:115], v[114:115], v[74:75], v[248:249]
	v_cvt_pk_bf16_f32 v116, v116, v117
	v_cvt_pk_bf16_f32 v117, v118, v119
	v_cvt_pk_bf16_f32 v118, v112, v113
	v_cvt_pk_bf16_f32 v119, v114, v115
	global_store_dwordx4 v[192:193], v[116:119], off offset:256
	s_waitcnt vmcnt(12)
	v_lshlrev_b32_e32 v188, 16, v226
	v_and_b32_e32 v189, 0xffff0000, v226
	v_lshlrev_b32_e32 v190, 16, v227
	v_and_b32_e32 v191, 0xffff0000, v227
	v_lshlrev_b32_e32 v246, 16, v228
	v_and_b32_e32 v247, 0xffff0000, v228
	v_lshlrev_b32_e32 v248, 16, v229
	v_and_b32_e32 v249, 0xffff0000, v229
	global_load_dwordx4 v[226:229], v[148:149], off offset:256
	v_lshl_add_u64 v[150:151], v[172:173], 1, v[144:145]
	v_pk_fma_f32 v[108:109], v[108:109], v[92:93], v[188:189]
	v_pk_fma_f32 v[110:111], v[110:111], v[94:95], v[190:191]
	v_pk_fma_f32 v[104:105], v[104:105], v[84:85], v[246:247]
	v_pk_fma_f32 v[106:107], v[106:107], v[86:87], v[248:249]
	v_cvt_pk_bf16_f32 v108, v108, v109
	v_cvt_pk_bf16_f32 v109, v110, v111
	v_cvt_pk_bf16_f32 v110, v104, v105
	v_cvt_pk_bf16_f32 v111, v106, v107
	global_store_dwordx4 v[150:151], v[108:111], off
	s_waitcnt vmcnt(13)
	v_lshlrev_b32_e32 v188, 16, v230
	v_and_b32_e32 v189, 0xffff0000, v230
	v_lshlrev_b32_e32 v190, 16, v231
	v_and_b32_e32 v191, 0xffff0000, v231
	v_lshlrev_b32_e32 v246, 16, v232
	v_and_b32_e32 v247, 0xffff0000, v232
	v_lshlrev_b32_e32 v248, 16, v233
	v_and_b32_e32 v249, 0xffff0000, v233
	v_lshl_add_u64 v[148:149], v[182:183], 1, v[144:145]
	global_load_dwordx4 v[230:233], v[148:149], off
	v_pk_fma_f32 v[100:101], v[100:101], v[76:77], v[188:189]
	v_pk_fma_f32 v[102:103], v[102:103], v[78:79], v[190:191]
	v_pk_fma_f32 v[96:97], v[96:97], v[72:73], v[246:247]
	v_pk_fma_f32 v[98:99], v[98:99], v[74:75], v[248:249]
	v_cvt_pk_bf16_f32 v100, v100, v101
	v_cvt_pk_bf16_f32 v101, v102, v103
	v_cvt_pk_bf16_f32 v102, v96, v97
	v_cvt_pk_bf16_f32 v103, v98, v99
	global_store_dwordx4 v[150:151], v[100:103], off offset:256
	s_waitcnt vmcnt(14)
	v_lshlrev_b32_e32 v188, 16, v234
	v_and_b32_e32 v189, 0xffff0000, v234
	v_lshlrev_b32_e32 v190, 16, v235
	v_and_b32_e32 v191, 0xffff0000, v235
	v_lshlrev_b32_e32 v246, 16, v236
	v_and_b32_e32 v247, 0xffff0000, v236
	v_lshlrev_b32_e32 v248, 16, v237
	v_and_b32_e32 v249, 0xffff0000, v237
	global_load_dwordx4 v[234:237], v[148:149], off offset:256
	v_lshl_add_u64 v[192:193], v[174:175], 1, v[144:145]
	v_pk_fma_f32 v[88:89], v[88:89], v[92:93], v[188:189]
	v_pk_fma_f32 v[90:91], v[90:91], v[94:95], v[190:191]
	v_pk_fma_f32 v[80:81], v[80:81], v[84:85], v[246:247]
	v_pk_fma_f32 v[82:83], v[82:83], v[86:87], v[248:249]
	v_cvt_pk_bf16_f32 v88, v88, v89
	v_cvt_pk_bf16_f32 v89, v90, v91
	v_cvt_pk_bf16_f32 v90, v80, v81
	v_cvt_pk_bf16_f32 v91, v82, v83
	global_store_dwordx4 v[192:193], v[88:91], off
	s_waitcnt vmcnt(15)
	v_lshlrev_b32_e32 v188, 16, v238
	v_and_b32_e32 v189, 0xffff0000, v238
	v_lshlrev_b32_e32 v190, 16, v239
	v_and_b32_e32 v191, 0xffff0000, v239
	v_lshlrev_b32_e32 v246, 16, v240
	v_and_b32_e32 v247, 0xffff0000, v240
	v_lshlrev_b32_e32 v248, 16, v241
	v_and_b32_e32 v249, 0xffff0000, v241
	v_pk_fma_f32 v[68:69], v[68:69], v[76:77], v[188:189]
	v_pk_fma_f32 v[70:71], v[70:71], v[78:79], v[190:191]
	v_pk_fma_f32 v[64:65], v[64:65], v[72:73], v[246:247]
	v_pk_fma_f32 v[66:67], v[66:67], v[74:75], v[248:249]
	v_cvt_pk_bf16_f32 v68, v68, v69
	v_cvt_pk_bf16_f32 v69, v70, v71
	v_cvt_pk_bf16_f32 v70, v64, v65
	v_cvt_pk_bf16_f32 v71, v66, v67
	global_store_dwordx4 v[192:193], v[68:71], off offset:256
	s_waitcnt vmcnt(15)
	v_lshlrev_b32_e32 v188, 16, v242
	v_and_b32_e32 v189, 0xffff0000, v242
	v_lshlrev_b32_e32 v190, 16, v243
	v_and_b32_e32 v191, 0xffff0000, v243
	v_lshlrev_b32_e32 v246, 16, v244
	v_and_b32_e32 v247, 0xffff0000, v244
	v_lshlrev_b32_e32 v248, 16, v245
	v_and_b32_e32 v249, 0xffff0000, v245
	v_lshl_add_u64 v[150:151], v[176:177], 1, v[144:145]
	v_pk_fma_f32 v[60:61], v[60:61], v[92:93], v[188:189]
	v_pk_fma_f32 v[62:63], v[62:63], v[94:95], v[190:191]
	v_pk_fma_f32 v[56:57], v[56:57], v[84:85], v[246:247]
	v_pk_fma_f32 v[58:59], v[58:59], v[86:87], v[248:249]
	v_cvt_pk_bf16_f32 v60, v60, v61
	v_cvt_pk_bf16_f32 v61, v62, v63
	v_cvt_pk_bf16_f32 v62, v56, v57
	v_cvt_pk_bf16_f32 v63, v58, v59
	global_store_dwordx4 v[150:151], v[60:63], off
	s_waitcnt vmcnt(15)
	v_lshlrev_b32_e32 v188, 16, v210
	v_and_b32_e32 v189, 0xffff0000, v210
	v_lshlrev_b32_e32 v190, 16, v211
	v_and_b32_e32 v191, 0xffff0000, v211
	v_lshlrev_b32_e32 v246, 16, v212
	v_and_b32_e32 v247, 0xffff0000, v212
	v_lshlrev_b32_e32 v248, 16, v213
	v_and_b32_e32 v249, 0xffff0000, v213
	v_pk_fma_f32 v[52:53], v[52:53], v[76:77], v[188:189]
	v_pk_fma_f32 v[54:55], v[54:55], v[78:79], v[190:191]
	v_pk_fma_f32 v[48:49], v[48:49], v[72:73], v[246:247]
	v_pk_fma_f32 v[50:51], v[50:51], v[74:75], v[248:249]
	v_cvt_pk_bf16_f32 v52, v52, v53
	v_cvt_pk_bf16_f32 v53, v54, v55
	v_cvt_pk_bf16_f32 v54, v48, v49
	v_cvt_pk_bf16_f32 v55, v50, v51
	global_store_dwordx4 v[150:151], v[52:55], off offset:256
	s_waitcnt vmcnt(14)
	v_lshlrev_b32_e32 v188, 16, v214
	v_and_b32_e32 v189, 0xffff0000, v214
	v_lshlrev_b32_e32 v190, 16, v215
	v_and_b32_e32 v191, 0xffff0000, v215
	v_lshlrev_b32_e32 v246, 16, v216
	v_and_b32_e32 v247, 0xffff0000, v216
	v_lshlrev_b32_e32 v248, 16, v217
	v_and_b32_e32 v249, 0xffff0000, v217
	v_lshl_add_u64 v[192:193], v[178:179], 1, v[144:145]
	v_pk_fma_f32 v[44:45], v[44:45], v[92:93], v[188:189]
	v_pk_fma_f32 v[46:47], v[46:47], v[94:95], v[190:191]
	v_pk_fma_f32 v[40:41], v[40:41], v[84:85], v[246:247]
	v_pk_fma_f32 v[42:43], v[42:43], v[86:87], v[248:249]
	v_cvt_pk_bf16_f32 v44, v44, v45
	v_cvt_pk_bf16_f32 v45, v46, v47
	v_cvt_pk_bf16_f32 v46, v40, v41
	v_cvt_pk_bf16_f32 v47, v42, v43
	global_store_dwordx4 v[192:193], v[44:47], off
	s_waitcnt vmcnt(13)
	v_lshlrev_b32_e32 v188, 16, v218
	v_and_b32_e32 v189, 0xffff0000, v218
	v_lshlrev_b32_e32 v190, 16, v219
	v_and_b32_e32 v191, 0xffff0000, v219
	v_lshlrev_b32_e32 v246, 16, v220
	v_and_b32_e32 v247, 0xffff0000, v220
	v_lshlrev_b32_e32 v248, 16, v221
	v_and_b32_e32 v249, 0xffff0000, v221
	v_pk_fma_f32 v[36:37], v[36:37], v[76:77], v[188:189]
	v_pk_fma_f32 v[38:39], v[38:39], v[78:79], v[190:191]
	v_pk_fma_f32 v[32:33], v[32:33], v[72:73], v[246:247]
	v_pk_fma_f32 v[34:35], v[34:35], v[74:75], v[248:249]
	v_cvt_pk_bf16_f32 v36, v36, v37
	v_cvt_pk_bf16_f32 v37, v38, v39
	v_cvt_pk_bf16_f32 v38, v32, v33
	v_cvt_pk_bf16_f32 v39, v34, v35
	global_store_dwordx4 v[192:193], v[36:39], off offset:256
	s_waitcnt vmcnt(12)
	v_lshlrev_b32_e32 v188, 16, v222
	v_and_b32_e32 v189, 0xffff0000, v222
	v_lshlrev_b32_e32 v190, 16, v223
	v_and_b32_e32 v191, 0xffff0000, v223
	v_lshlrev_b32_e32 v246, 16, v224
	v_and_b32_e32 v247, 0xffff0000, v224
	v_lshlrev_b32_e32 v248, 16, v225
	v_and_b32_e32 v249, 0xffff0000, v225
	v_lshl_add_u64 v[150:151], v[180:181], 1, v[144:145]
	v_pk_fma_f32 v[28:29], v[28:29], v[92:93], v[188:189]
	v_pk_fma_f32 v[30:31], v[30:31], v[94:95], v[190:191]
	v_pk_fma_f32 v[24:25], v[24:25], v[84:85], v[246:247]
	v_pk_fma_f32 v[26:27], v[26:27], v[86:87], v[248:249]
	v_cvt_pk_bf16_f32 v28, v28, v29
	v_cvt_pk_bf16_f32 v29, v30, v31
	v_cvt_pk_bf16_f32 v30, v24, v25
	v_cvt_pk_bf16_f32 v31, v26, v27
	global_store_dwordx4 v[150:151], v[28:31], off
	s_waitcnt vmcnt(11)
	v_lshlrev_b32_e32 v188, 16, v226
	v_and_b32_e32 v189, 0xffff0000, v226
	v_lshlrev_b32_e32 v190, 16, v227
	v_and_b32_e32 v191, 0xffff0000, v227
	v_lshlrev_b32_e32 v246, 16, v228
	v_and_b32_e32 v247, 0xffff0000, v228
	v_lshlrev_b32_e32 v248, 16, v229
	v_and_b32_e32 v249, 0xffff0000, v229
	v_pk_fma_f32 v[20:21], v[20:21], v[76:77], v[188:189]
	v_pk_fma_f32 v[22:23], v[22:23], v[78:79], v[190:191]
	v_pk_fma_f32 v[16:17], v[16:17], v[72:73], v[246:247]
	v_pk_fma_f32 v[18:19], v[18:19], v[74:75], v[248:249]
	v_cvt_pk_bf16_f32 v20, v20, v21
	v_cvt_pk_bf16_f32 v21, v22, v23
	v_cvt_pk_bf16_f32 v22, v16, v17
	v_cvt_pk_bf16_f32 v23, v18, v19
	global_store_dwordx4 v[150:151], v[20:23], off offset:256
	s_waitcnt vmcnt(10)
	v_lshlrev_b32_e32 v188, 16, v230
	v_and_b32_e32 v189, 0xffff0000, v230
	v_lshlrev_b32_e32 v190, 16, v231
	v_and_b32_e32 v191, 0xffff0000, v231
	v_lshlrev_b32_e32 v246, 16, v232
	v_and_b32_e32 v247, 0xffff0000, v232
	v_lshlrev_b32_e32 v248, 16, v233
	v_and_b32_e32 v249, 0xffff0000, v233
	v_lshl_add_u64 v[192:193], v[182:183], 1, v[144:145]
	v_pk_fma_f32 v[12:13], v[12:13], v[92:93], v[188:189]
	v_pk_fma_f32 v[14:15], v[14:15], v[94:95], v[190:191]
	v_pk_fma_f32 v[8:9], v[8:9], v[84:85], v[246:247]
	v_pk_fma_f32 v[10:11], v[10:11], v[86:87], v[248:249]
	v_cvt_pk_bf16_f32 v12, v12, v13
	v_cvt_pk_bf16_f32 v13, v14, v15
	v_cvt_pk_bf16_f32 v14, v8, v9
	v_cvt_pk_bf16_f32 v15, v10, v11
	global_store_dwordx4 v[192:193], v[12:15], off
	s_waitcnt vmcnt(9)
	v_lshlrev_b32_e32 v188, 16, v234
	v_and_b32_e32 v189, 0xffff0000, v234
	v_lshlrev_b32_e32 v190, 16, v235
	v_and_b32_e32 v191, 0xffff0000, v235
	v_lshlrev_b32_e32 v246, 16, v236
	v_and_b32_e32 v247, 0xffff0000, v236
	v_lshlrev_b32_e32 v248, 16, v237
	v_and_b32_e32 v249, 0xffff0000, v237
	v_pk_fma_f32 v[4:5], v[4:5], v[76:77], v[188:189]
	v_pk_fma_f32 v[6:7], v[6:7], v[78:79], v[190:191]
	v_pk_fma_f32 v[0:1], v[0:1], v[72:73], v[246:247]
	v_pk_fma_f32 v[2:3], v[2:3], v[74:75], v[248:249]
	v_cvt_pk_bf16_f32 v4, v4, v5
	v_cvt_pk_bf16_f32 v5, v6, v7
	v_cvt_pk_bf16_f32 v6, v0, v1
	v_cvt_pk_bf16_f32 v7, v2, v3
	global_store_dwordx4 v[192:193], v[4:7], off offset:256
	s_branch .Lwo_epi_done
.Lwo_epi_f32:
	v_lshl_add_u64 v[146:147], v[188:189], 2, s[38:39]
	v_lshl_add_u64 v[148:149], v[168:169], 2, v[146:147]
	global_load_dwordx4 v[210:213], v[148:149], off
	global_load_dwordx4 v[214:217], v[148:149], off offset:16
	global_load_dwordx4 v[218:221], v[148:149], off offset:512
	global_load_dwordx4 v[222:225], v[148:149], off offset:528
	v_lshl_add_u64 v[148:149], v[170:171], 2, v[146:147]
	global_load_dwordx4 v[226:229], v[148:149], off
	global_load_dwordx4 v[230:233], v[148:149], off offset:16
	global_load_dwordx4 v[234:237], v[148:149], off offset:512
	global_load_dwordx4 v[238:241], v[148:149], off offset:528
	v_lshl_add_u64 v[148:149], v[172:173], 2, v[146:147]
	global_load_dwordx4 v[242:245], v[148:149], off
	global_load_dwordx4 v[246:249], v[148:149], off offset:16
	s_waitcnt vmcnt(8)
	v_pk_fma_f32 v[140:141], v[140:141], v[92:93], v[210:211]
	v_pk_fma_f32 v[142:143], v[142:143], v[94:95], v[212:213]
	v_pk_fma_f32 v[136:137], v[136:137], v[84:85], v[214:215]
	v_pk_fma_f32 v[138:139], v[138:139], v[86:87], v[216:217]
	global_load_dwordx4 v[210:213], v[148:149], off offset:512
	global_load_dwordx4 v[214:217], v[148:149], off offset:528
	v_lshl_add_u64 v[150:151], v[168:169], 1, v[144:145]
	v_cvt_pk_bf16_f32 v140, v140, v141
	v_cvt_pk_bf16_f32 v141, v142, v143
	v_cvt_pk_bf16_f32 v142, v136, v137
	v_cvt_pk_bf16_f32 v143, v138, v139
	global_store_dwordx4 v[150:151], v[140:143], off
	s_waitcnt vmcnt(9)
	v_pk_fma_f32 v[132:133], v[132:133], v[76:77], v[218:219]
	v_pk_fma_f32 v[134:135], v[134:135], v[78:79], v[220:221]
	v_pk_fma_f32 v[128:129], v[128:129], v[72:73], v[222:223]
	v_pk_fma_f32 v[130:131], v[130:131], v[74:75], v[224:225]
	v_lshl_add_u64 v[148:149], v[174:175], 2, v[146:147]
	global_load_dwordx4 v[218:221], v[148:149], off
	global_load_dwordx4 v[222:225], v[148:149], off offset:16
	v_cvt_pk_bf16_f32 v132, v132, v133
	v_cvt_pk_bf16_f32 v133, v134, v135
	v_cvt_pk_bf16_f32 v134, v128, v129
	v_cvt_pk_bf16_f32 v135, v130, v131
	global_store_dwordx4 v[150:151], v[132:135], off offset:256
	s_waitcnt vmcnt(10)
	v_pk_fma_f32 v[124:125], v[124:125], v[92:93], v[226:227]
	v_pk_fma_f32 v[126:127], v[126:127], v[94:95], v[228:229]
	v_pk_fma_f32 v[120:121], v[120:121], v[84:85], v[230:231]
	v_pk_fma_f32 v[122:123], v[122:123], v[86:87], v[232:233]
	global_load_dwordx4 v[226:229], v[148:149], off offset:512
	global_load_dwordx4 v[230:233], v[148:149], off offset:528
	v_lshl_add_u64 v[192:193], v[170:171], 1, v[144:145]
	v_cvt_pk_bf16_f32 v124, v124, v125
	v_cvt_pk_bf16_f32 v125, v126, v127
	v_cvt_pk_bf16_f32 v126, v120, v121
	v_cvt_pk_bf16_f32 v127, v122, v123
	global_store_dwordx4 v[192:193], v[124:127], off
	s_waitcnt vmcnt(11)
	v_pk_fma_f32 v[116:117], v[116:117], v[76:77], v[234:235]
	v_pk_fma_f32 v[118:119], v[118:119], v[78:79], v[236:237]
	v_pk_fma_f32 v[112:113], v[112:113], v[72:73], v[238:239]
	v_pk_fma_f32 v[114:115], v[114:115], v[74:75], v[240:241]
	v_lshl_add_u64 v[148:149], v[176:177], 2, v[146:147]
	global_load_dwordx4 v[234:237], v[148:149], off
	global_load_dwordx4 v[238:241], v[148:149], off offset:16
	v_cvt_pk_bf16_f32 v116, v116, v117
	v_cvt_pk_bf16_f32 v117, v118, v119
	v_cvt_pk_bf16_f32 v118, v112, v113
	v_cvt_pk_bf16_f32 v119, v114, v115
	global_store_dwordx4 v[192:193], v[116:119], off offset:256
	s_waitcnt vmcnt(12)
	v_pk_fma_f32 v[108:109], v[108:109], v[92:93], v[242:243]
	v_pk_fma_f32 v[110:111], v[110:111], v[94:95], v[244:245]
	v_pk_fma_f32 v[104:105], v[104:105], v[84:85], v[246:247]
	v_pk_fma_f32 v[106:107], v[106:107], v[86:87], v[248:249]
	global_load_dwordx4 v[242:245], v[148:149], off offset:512
	global_load_dwordx4 v[246:249], v[148:149], off offset:528
	v_lshl_add_u64 v[150:151], v[172:173], 1, v[144:145]
	v_cvt_pk_bf16_f32 v108, v108, v109
	v_cvt_pk_bf16_f32 v109, v110, v111
	v_cvt_pk_bf16_f32 v110, v104, v105
	v_cvt_pk_bf16_f32 v111, v106, v107
	global_store_dwordx4 v[150:151], v[108:111], off
	s_waitcnt vmcnt(13)
	v_pk_fma_f32 v[100:101], v[100:101], v[76:77], v[210:211]
	v_pk_fma_f32 v[102:103], v[102:103], v[78:79], v[212:213]
	v_pk_fma_f32 v[96:97], v[96:97], v[72:73], v[214:215]
	v_pk_fma_f32 v[98:99], v[98:99], v[74:75], v[216:217]
	v_lshl_add_u64 v[148:149], v[178:179], 2, v[146:147]
	global_load_dwordx4 v[210:213], v[148:149], off
	global_load_dwordx4 v[214:217], v[148:149], off offset:16
	v_cvt_pk_bf16_f32 v100, v100, v101
	v_cvt_pk_bf16_f32 v101, v102, v103
	v_cvt_pk_bf16_f32 v102, v96, v97
	v_cvt_pk_bf16_f32 v103, v98, v99
	global_store_dwordx4 v[150:151], v[100:103], off offset:256
	s_waitcnt vmcnt(13)
	v_pk_fma_f32 v[88:89], v[88:89], v[92:93], v[218:219]
	v_pk_fma_f32 v[90:91], v[90:91], v[94:95], v[220:221]
	v_pk_fma_f32 v[80:81], v[80:81], v[84:85], v[222:223]
	v_pk_fma_f32 v[82:83], v[82:83], v[86:87], v[224:225]
	global_load_dwordx4 v[218:221], v[148:149], off offset:512
	global_load_dwordx4 v[222:225], v[148:149], off offset:528
	v_lshl_add_u64 v[192:193], v[174:175], 1, v[144:145]
	v_cvt_pk_bf16_f32 v88, v88, v89
	v_cvt_pk_bf16_f32 v89, v90, v91
	v_cvt_pk_bf16_f32 v90, v80, v81
	v_cvt_pk_bf16_f32 v91, v82, v83
	global_store_dwordx4 v[192:193], v[88:91], off
	s_waitcnt vmcnt(13)
	v_pk_fma_f32 v[68:69], v[68:69], v[76:77], v[226:227]
	v_pk_fma_f32 v[70:71], v[70:71], v[78:79], v[228:229]
	v_pk_fma_f32 v[64:65], v[64:65], v[72:73], v[230:231]
	v_pk_fma_f32 v[66:67], v[66:67], v[74:75], v[232:233]
	v_lshl_add_u64 v[148:149], v[180:181], 2, v[146:147]
	global_load_dwordx4 v[226:229], v[148:149], off
	global_load_dwordx4 v[230:233], v[148:149], off offset:16
	v_cvt_pk_bf16_f32 v68, v68, v69
	v_cvt_pk_bf16_f32 v69, v70, v71
	v_cvt_pk_bf16_f32 v70, v64, v65
	v_cvt_pk_bf16_f32 v71, v66, v67
	global_store_dwordx4 v[192:193], v[68:71], off offset:256
	s_waitcnt vmcnt(13)
	v_pk_fma_f32 v[60:61], v[60:61], v[92:93], v[234:235]
	v_pk_fma_f32 v[62:63], v[62:63], v[94:95], v[236:237]
	v_pk_fma_f32 v[56:57], v[56:57], v[84:85], v[238:239]
	v_pk_fma_f32 v[58:59], v[58:59], v[86:87], v[240:241]
	global_load_dwordx4 v[234:237], v[148:149], off offset:512
	global_load_dwordx4 v[238:241], v[148:149], off offset:528
	v_lshl_add_u64 v[150:151], v[176:177], 1, v[144:145]
	v_cvt_pk_bf16_f32 v60, v60, v61
	v_cvt_pk_bf16_f32 v61, v62, v63
	v_cvt_pk_bf16_f32 v62, v56, v57
	v_cvt_pk_bf16_f32 v63, v58, v59
	global_store_dwordx4 v[150:151], v[60:63], off
	s_waitcnt vmcnt(13)
	v_pk_fma_f32 v[52:53], v[52:53], v[76:77], v[242:243]
	v_pk_fma_f32 v[54:55], v[54:55], v[78:79], v[244:245]
	v_pk_fma_f32 v[48:49], v[48:49], v[72:73], v[246:247]
	v_pk_fma_f32 v[50:51], v[50:51], v[74:75], v[248:249]
	v_lshl_add_u64 v[148:149], v[182:183], 2, v[146:147]
	global_load_dwordx4 v[242:245], v[148:149], off
	global_load_dwordx4 v[246:249], v[148:149], off offset:16
	v_cvt_pk_bf16_f32 v52, v52, v53
	v_cvt_pk_bf16_f32 v53, v54, v55
	v_cvt_pk_bf16_f32 v54, v48, v49
	v_cvt_pk_bf16_f32 v55, v50, v51
	global_store_dwordx4 v[150:151], v[52:55], off offset:256
	s_waitcnt vmcnt(13)
	v_pk_fma_f32 v[44:45], v[44:45], v[92:93], v[210:211]
	v_pk_fma_f32 v[46:47], v[46:47], v[94:95], v[212:213]
	v_pk_fma_f32 v[40:41], v[40:41], v[84:85], v[214:215]
	v_pk_fma_f32 v[42:43], v[42:43], v[86:87], v[216:217]
	global_load_dwordx4 v[210:213], v[148:149], off offset:512
	global_load_dwordx4 v[214:217], v[148:149], off offset:528
	v_lshl_add_u64 v[192:193], v[178:179], 1, v[144:145]
	v_cvt_pk_bf16_f32 v44, v44, v45
	v_cvt_pk_bf16_f32 v45, v46, v47
	v_cvt_pk_bf16_f32 v46, v40, v41
	v_cvt_pk_bf16_f32 v47, v42, v43
	global_store_dwordx4 v[192:193], v[44:47], off
	s_waitcnt vmcnt(13)
	v_pk_fma_f32 v[36:37], v[36:37], v[76:77], v[218:219]
	v_pk_fma_f32 v[38:39], v[38:39], v[78:79], v[220:221]
	v_pk_fma_f32 v[32:33], v[32:33], v[72:73], v[222:223]
	v_pk_fma_f32 v[34:35], v[34:35], v[74:75], v[224:225]
	v_cvt_pk_bf16_f32 v36, v36, v37
	v_cvt_pk_bf16_f32 v37, v38, v39
	v_cvt_pk_bf16_f32 v38, v32, v33
	v_cvt_pk_bf16_f32 v39, v34, v35
	global_store_dwordx4 v[192:193], v[36:39], off offset:256
	s_waitcnt vmcnt(11)
	v_pk_fma_f32 v[28:29], v[28:29], v[92:93], v[226:227]
	v_pk_fma_f32 v[30:31], v[30:31], v[94:95], v[228:229]
	v_pk_fma_f32 v[24:25], v[24:25], v[84:85], v[230:231]
	v_pk_fma_f32 v[26:27], v[26:27], v[86:87], v[232:233]
	v_lshl_add_u64 v[150:151], v[180:181], 1, v[144:145]
	v_cvt_pk_bf16_f32 v28, v28, v29
	v_cvt_pk_bf16_f32 v29, v30, v31
	v_cvt_pk_bf16_f32 v30, v24, v25
	v_cvt_pk_bf16_f32 v31, v26, v27
	global_store_dwordx4 v[150:151], v[28:31], off
	s_waitcnt vmcnt(9)
	v_pk_fma_f32 v[20:21], v[20:21], v[76:77], v[234:235]
	v_pk_fma_f32 v[22:23], v[22:23], v[78:79], v[236:237]
	v_pk_fma_f32 v[16:17], v[16:17], v[72:73], v[238:239]
	v_pk_fma_f32 v[18:19], v[18:19], v[74:75], v[240:241]
	v_cvt_pk_bf16_f32 v20, v20, v21
	v_cvt_pk_bf16_f32 v21, v22, v23
	v_cvt_pk_bf16_f32 v22, v16, v17
	v_cvt_pk_bf16_f32 v23, v18, v19
	global_store_dwordx4 v[150:151], v[20:23], off offset:256
	s_waitcnt vmcnt(7)
	v_pk_fma_f32 v[12:13], v[12:13], v[92:93], v[242:243]
	v_pk_fma_f32 v[14:15], v[14:15], v[94:95], v[244:245]
	v_pk_fma_f32 v[8:9], v[8:9], v[84:85], v[246:247]
	v_pk_fma_f32 v[10:11], v[10:11], v[86:87], v[248:249]
	v_lshl_add_u64 v[192:193], v[182:183], 1, v[144:145]
	v_cvt_pk_bf16_f32 v12, v12, v13
	v_cvt_pk_bf16_f32 v13, v14, v15
	v_cvt_pk_bf16_f32 v14, v8, v9
	v_cvt_pk_bf16_f32 v15, v10, v11
	global_store_dwordx4 v[192:193], v[12:15], off
	s_waitcnt vmcnt(5)
	v_pk_fma_f32 v[4:5], v[4:5], v[76:77], v[210:211]
	v_pk_fma_f32 v[6:7], v[6:7], v[78:79], v[212:213]
	v_pk_fma_f32 v[0:1], v[0:1], v[72:73], v[214:215]
	v_pk_fma_f32 v[2:3], v[2:3], v[74:75], v[216:217]
	v_cvt_pk_bf16_f32 v4, v4, v5
	v_cvt_pk_bf16_f32 v5, v6, v7
	v_cvt_pk_bf16_f32 v6, v0, v1
	v_cvt_pk_bf16_f32 v7, v2, v3
	global_store_dwordx4 v[192:193], v[4:7], off offset:256
.Lwo_epi_done:
	s_and_b64 vcc, exec, s[42:43]
	s_mov_b32 s4, s0
	s_mov_b32 s20, s16
	s_mov_b64 s[38:39], s[34:35]
	s_mov_b64 s[22:23], s[24:25]
	s_cbranch_vccz .LBB0_558
